# census words after the first grid barrier read together (8 serialized round trips removed), code padded so every later loop keeps its byte offset
# speedup vs baseline: 1.0029x; 1.0022x over previous
; __device__ __forceinline__ unsigned xb_ld(unsigned* p)              { return __hip_atomic_load(p, __ATOMIC_RELAXED, __HIP_MEMORY_SCOPE_AGENT); }
; __global__ void __launch_bounds__(NTHR, 2) fwd_kernel(Args a) {
;     ...
;     if (threadIdx.x == 0) { bool even = (G == 256);
;         for (unsigned j = 0; j < 8; ++j) even = even && (xb_ld(&barw_[XB_XCNT(j)]) == 32u);
;         vcw[1] = even ? vcw[0] * 8u + xbar.x : (unsigned)bid; }
;     __syncthreads();
.LBB0_225:
	s_or_b64 exec, exec, s[2:3]
	s_waitcnt lgkmcnt(0)
	s_barrier
	s_mov_b64 s[2:3], exec
	v_readlane_b32 s4, v246, 2
	v_readlane_b32 s5, v246, 3
	s_and_b64 s[4:5], s[2:3], s[4:5]
	s_mov_b64 exec, s[4:5]
	s_cbranch_execz .LBB0_237
	s_cmpk_lg_i32 s82, 0x100
	v_mov_b32_e32 v0, s62
	s_cbranch_scc1 .LBB0_236
	v_mov_b32_e32 v1, 0x221e4000
	global_load_dword v248, v1, s[0:1] offset:1024 sc1
	global_load_dword v249, v1, s[0:1] offset:1280 sc1
	global_load_dword v250, v1, s[0:1] offset:1536 sc1
	global_load_dword v251, v1, s[0:1] offset:1792 sc1
	global_load_dword v252, v1, s[0:1] offset:2048 sc1
	global_load_dword v253, v1, s[0:1] offset:2304 sc1
	global_load_dword v254, v1, s[0:1] offset:2560 sc1
	global_load_dword v255, v1, s[0:1] offset:2816 sc1
	s_waitcnt vmcnt(0)
	v_xor_b32_e32 v248, 32, v248
	v_xor_b32_e32 v249, 32, v249
	v_xor_b32_e32 v250, 32, v250
	v_xor_b32_e32 v251, 32, v251
	v_xor_b32_e32 v252, 32, v252
	v_xor_b32_e32 v253, 32, v253
	v_xor_b32_e32 v254, 32, v254
	v_xor_b32_e32 v255, 32, v255
	v_or3_b32 v248, v248, v249, v250
	v_or3_b32 v251, v251, v252, v253
	v_or3_b32 v248, v248, v254, v255
	v_or_b32_e32 v248, v248, v251
	v_cmp_ne_u32_e32 vcc, 0, v248
	v_mov_b32_e32 v0, s62
	s_cbranch_vccnz .LBB0_236
	s_add_i32 s4, 0, 0x23fd0
	v_mov_b32_e32 v0, s4
	ds_read_b32 v0, v0
	s_waitcnt lgkmcnt(0)
	v_lshlrev_b32_e32 v0, 3, v0
	v_add_u32_e32 v0, s49, v0
.LBB0_236:
	s_nop 0
	s_nop 0
	s_nop 0
	s_nop 0
	s_nop 0
	s_nop 0
	s_nop 0
	s_nop 0
	s_nop 0
	s_nop 0
	s_nop 0
	s_nop 0
	s_nop 0
	s_nop 0
	s_nop 0
	s_nop 0
	s_nop 0
	s_nop 0
	s_nop 0
	s_add_i32 s4, 0, 0x23fd4
	v_mov_b32_e32 v1, s4
	ds_write_b32 v1, v0
